# kv_b and out-proj final epilogues: 8 rsq loads hoisted, counted vmcnt (on top of attention deferred-MFMA version)
# baseline (speedup 1.0000x reference)
; __device__ __forceinline__ u32x4 pack8(f32x4 v0, f32x4 v1) { u32x4 w; w.x = cvt_pk_bf16(v0[0], v0[1]); w.y = cvt_pk_bf16(v0[2], v0[3]); w.z = cvt_pk_bf16(v1[0], v1[1]); w.w = cvt_pk_bf16(v1[2], v1[3]); return w; }
;     __device__ __forceinline__ void operator()(EPI_ARGS) const {
; #pragma unroll
;         for (int ai = 0; ai < 2; ++ai)
; #pragma unroll
;             for (int m = 0; m < 4; ++m) { const int row = EPI_ROW(ai, m); const float rstd = rsq ? __builtin_amdgcn_rsqf(rsq[row] * inv_n + RMS_EPS) : 1.f;
; #pragma unroll
;                 for (int bj = 0; bj < 2; ++bj) *(u32x4*)(O + (size_t)row * ld + EPI_COL(bj)) = pack8(acc[ai][bj][m][0] * rstd, acc[ai][bj][m][1] * rstd);
;                 asm volatile("" ::: "memory"); }
;     }
.LBB0_357:
	v_lshl_add_u32 v136, s94, 8, v140
	v_ashrrev_i32_e32 v137, 31, v136
	v_lshl_add_u64 v[150:151], v[136:137], 2, s[30:31]
	global_load_dword v216, v[150:151], off
	global_load_dword v217, v[150:151], off offset:64
	global_load_dword v218, v[150:151], off offset:128
	global_load_dword v219, v[150:151], off offset:192
	global_load_dword v220, v[150:151], off offset:512
	global_load_dword v221, v[150:151], off offset:576
	global_load_dword v222, v[150:151], off offset:640
	global_load_dword v223, v[150:151], off offset:704
	v_lshl_or_b32 v148, s93, 8, v141
	v_ashrrev_i32_e32 v149, 31, v148
	s_andn2_b64 vcc, exec, s[4:5]
	s_waitcnt vmcnt(7)
	v_fmamk_f32 v137, v216, 0x3b800000, v147
	v_rsq_f32_e32 v150, v137
	s_nop 0
	v_pk_mul_f32 v[126:127], v[126:127], v[150:151] op_sel_hi:[1,0]
	v_pk_mul_f32 v[124:125], v[124:125], v[150:151] op_sel_hi:[1,0]
	v_pk_mul_f32 v[120:121], v[120:121], v[150:151] op_sel_hi:[1,0]
	v_pk_mul_f32 v[122:123], v[122:123], v[150:151] op_sel_hi:[1,0]
	v_cvt_pk_bf16_f32 v124, v124, v125
	v_cvt_pk_bf16_f32 v125, v126, v127
	v_cvt_pk_bf16_f32 v126, v120, v121
	v_mov_b64_e32 v[120:121], s[86:87]
	v_cvt_pk_bf16_f32 v127, v122, v123
	v_mad_i64_i32 v[152:153], s[8:9], v136, s84, v[120:121]
	v_lshlrev_b64 v[122:123], 1, v[148:149]
	v_lshl_add_u64 v[148:149], v[152:153], 0, v[122:123]
	global_store_dwordx4 v[148:149], v[124:127], off
	v_pk_mul_f32 v[116:117], v[116:117], v[150:151] op_sel_hi:[1,0]
	v_pk_mul_f32 v[118:119], v[118:119], v[150:151] op_sel_hi:[1,0]
	v_pk_mul_f32 v[124:125], v[114:115], v[150:151] op_sel_hi:[1,0]
	v_pk_mul_f32 v[114:115], v[112:113], v[150:151] op_sel_hi:[1,0]
	v_cvt_pk_bf16_f32 v112, v116, v117
	v_cvt_pk_bf16_f32 v113, v118, v119
	s_nop 0
	v_cvt_pk_bf16_f32 v114, v114, v115
	v_cvt_pk_bf16_f32 v115, v124, v125
	global_store_dwordx4 v[148:149], v[112:115], off offset:256
	s_nop 1
	v_or_b32_e32 v112, 16, v136
	v_ashrrev_i32_e32 v113, 31, v112
	v_lshl_add_u64 v[114:115], v[112:113], 2, s[30:31]
	s_nop 1
	s_waitcnt vmcnt(8)
	v_fmamk_f32 v113, v217, 0x3b800000, v147
	v_rsq_f32_e32 v114, v113
	s_nop 0
	v_pk_mul_f32 v[108:109], v[108:109], v[114:115] op_sel_hi:[1,0]
	v_pk_mul_f32 v[116:117], v[106:107], v[114:115] op_sel_hi:[1,0]
	v_pk_mul_f32 v[106:107], v[104:105], v[114:115] op_sel_hi:[1,0]
	v_cvt_pk_bf16_f32 v104, v108, v109
	v_mad_i64_i32 v[108:109], s[8:9], v112, s84, v[120:121]
	v_pk_mul_f32 v[110:111], v[110:111], v[114:115] op_sel_hi:[1,0]
	v_lshl_add_u64 v[108:109], v[108:109], 0, v[122:123]
	v_cvt_pk_bf16_f32 v105, v110, v111
	v_cvt_pk_bf16_f32 v106, v106, v107
	v_cvt_pk_bf16_f32 v107, v116, v117
	global_store_dwordx4 v[108:109], v[104:107], off
	v_pk_mul_f32 v[100:101], v[100:101], v[114:115] op_sel_hi:[1,0]
	v_pk_mul_f32 v[102:103], v[102:103], v[114:115] op_sel_hi:[1,0]
	v_pk_mul_f32 v[104:105], v[98:99], v[114:115] op_sel_hi:[1,0]
	v_pk_mul_f32 v[98:99], v[96:97], v[114:115] op_sel_hi:[1,0]
	v_cvt_pk_bf16_f32 v96, v100, v101
	v_cvt_pk_bf16_f32 v97, v102, v103
	s_nop 0
	v_cvt_pk_bf16_f32 v98, v98, v99
	v_cvt_pk_bf16_f32 v99, v104, v105
	global_store_dwordx4 v[108:109], v[96:99], off offset:256
	s_nop 1
	v_or_b32_e32 v96, 32, v136
	v_ashrrev_i32_e32 v97, 31, v96
	v_lshl_add_u64 v[98:99], v[96:97], 2, s[30:31]
	s_nop 1
	s_waitcnt vmcnt(9)
	v_fmamk_f32 v97, v218, 0x3b800000, v147
	v_rsq_f32_e32 v98, v97
	s_nop 0
	v_pk_mul_f32 v[92:93], v[92:93], v[98:99] op_sel_hi:[1,0]
	v_pk_mul_f32 v[100:101], v[90:91], v[98:99] op_sel_hi:[1,0]
	v_pk_mul_f32 v[90:91], v[88:89], v[98:99] op_sel_hi:[1,0]
	v_cvt_pk_bf16_f32 v88, v92, v93
	v_mad_i64_i32 v[92:93], s[8:9], v96, s84, v[120:121]
	v_pk_mul_f32 v[94:95], v[94:95], v[98:99] op_sel_hi:[1,0]
	v_lshl_add_u64 v[92:93], v[92:93], 0, v[122:123]
	v_cvt_pk_bf16_f32 v89, v94, v95
	v_cvt_pk_bf16_f32 v90, v90, v91
	v_cvt_pk_bf16_f32 v91, v100, v101
	global_store_dwordx4 v[92:93], v[88:91], off
	v_pk_mul_f32 v[84:85], v[84:85], v[98:99] op_sel_hi:[1,0]
	v_pk_mul_f32 v[86:87], v[86:87], v[98:99] op_sel_hi:[1,0]
	v_pk_mul_f32 v[88:89], v[82:83], v[98:99] op_sel_hi:[1,0]
	v_pk_mul_f32 v[82:83], v[80:81], v[98:99] op_sel_hi:[1,0]
	v_cvt_pk_bf16_f32 v80, v84, v85
	v_cvt_pk_bf16_f32 v81, v86, v87
	s_nop 0
	v_cvt_pk_bf16_f32 v82, v82, v83
	v_cvt_pk_bf16_f32 v83, v88, v89
	global_store_dwordx4 v[92:93], v[80:83], off offset:256
	s_nop 1
	v_or_b32_e32 v80, 48, v136
	v_ashrrev_i32_e32 v81, 31, v80
	v_lshl_add_u64 v[82:83], v[80:81], 2, s[30:31]
	s_nop 1
	s_waitcnt vmcnt(10)
	v_fmamk_f32 v81, v219, 0x3b800000, v147
	v_rsq_f32_e32 v82, v81
	s_nop 0
	v_pk_mul_f32 v[76:77], v[76:77], v[82:83] op_sel_hi:[1,0]
	v_pk_mul_f32 v[84:85], v[74:75], v[82:83] op_sel_hi:[1,0]
	v_pk_mul_f32 v[74:75], v[72:73], v[82:83] op_sel_hi:[1,0]
	v_cvt_pk_bf16_f32 v72, v76, v77
	v_mad_i64_i32 v[76:77], s[8:9], v80, s84, v[120:121]
	v_pk_mul_f32 v[78:79], v[78:79], v[82:83] op_sel_hi:[1,0]
	v_lshl_add_u64 v[76:77], v[76:77], 0, v[122:123]
	v_cvt_pk_bf16_f32 v73, v78, v79
	v_cvt_pk_bf16_f32 v74, v74, v75
	v_cvt_pk_bf16_f32 v75, v84, v85
	global_store_dwordx4 v[76:77], v[72:75], off
	v_pk_mul_f32 v[68:69], v[68:69], v[82:83] op_sel_hi:[1,0]
	v_pk_mul_f32 v[70:71], v[70:71], v[82:83] op_sel_hi:[1,0]
	v_pk_mul_f32 v[72:73], v[66:67], v[82:83] op_sel_hi:[1,0]
	v_pk_mul_f32 v[66:67], v[64:65], v[82:83] op_sel_hi:[1,0]
	v_cvt_pk_bf16_f32 v64, v68, v69
	v_cvt_pk_bf16_f32 v65, v70, v71
	s_nop 0
	v_cvt_pk_bf16_f32 v66, v66, v67
	v_cvt_pk_bf16_f32 v67, v72, v73
	global_store_dwordx4 v[76:77], v[64:67], off offset:256
	s_nop 1
	v_add_u32_e32 v64, 0x80, v136
	v_ashrrev_i32_e32 v65, 31, v64
	v_lshl_add_u64 v[66:67], v[64:65], 2, s[30:31]
	s_nop 1
	s_waitcnt vmcnt(11)
; __device__ __forceinline__ u32x4 pack8(f32x4 v0, f32x4 v1) { u32x4 w; w.x = cvt_pk_bf16(v0[0], v0[1]); w.y = cvt_pk_bf16(v0[2], v0[3]); w.z = cvt_pk_bf16(v1[0], v1[1]); w.w = cvt_pk_bf16(v1[2], v1[3]); return w; }
;     __device__ __forceinline__ void operator()(EPI_ARGS) const {
; #pragma unroll
;         for (int ai = 0; ai < 2; ++ai)
; #pragma unroll
;             for (int m = 0; m < 4; ++m) { const int row = EPI_ROW(ai, m); const float rstd = rsq ? __builtin_amdgcn_rsqf(rsq[row] * inv_n + RMS_EPS) : 1.f;
; #pragma unroll
;                 for (int bj = 0; bj < 2; ++bj) *(u32x4*)(O + (size_t)row * ld + EPI_COL(bj)) = pack8(acc[ai][bj][m][0] * rstd, acc[ai][bj][m][1] * rstd);
;                 asm volatile("" ::: "memory"); }
;     }
	v_fmamk_f32 v65, v220, 0x3b800000, v147
	v_rsq_f32_e32 v66, v65
	s_nop 0
	v_pk_mul_f32 v[60:61], v[60:61], v[66:67] op_sel_hi:[1,0]
	v_pk_mul_f32 v[68:69], v[58:59], v[66:67] op_sel_hi:[1,0]
	v_pk_mul_f32 v[58:59], v[56:57], v[66:67] op_sel_hi:[1,0]
	v_cvt_pk_bf16_f32 v56, v60, v61
	v_mad_i64_i32 v[60:61], s[8:9], v64, s84, v[120:121]
	v_pk_mul_f32 v[62:63], v[62:63], v[66:67] op_sel_hi:[1,0]
	v_lshl_add_u64 v[60:61], v[60:61], 0, v[122:123]
	v_cvt_pk_bf16_f32 v57, v62, v63
	v_cvt_pk_bf16_f32 v58, v58, v59
	v_cvt_pk_bf16_f32 v59, v68, v69
	global_store_dwordx4 v[60:61], v[56:59], off
	v_pk_mul_f32 v[52:53], v[52:53], v[66:67] op_sel_hi:[1,0]
	v_pk_mul_f32 v[54:55], v[54:55], v[66:67] op_sel_hi:[1,0]
	v_pk_mul_f32 v[56:57], v[50:51], v[66:67] op_sel_hi:[1,0]
	v_pk_mul_f32 v[50:51], v[48:49], v[66:67] op_sel_hi:[1,0]
	v_cvt_pk_bf16_f32 v48, v52, v53
	v_cvt_pk_bf16_f32 v49, v54, v55
	s_nop 0
	v_cvt_pk_bf16_f32 v50, v50, v51
	v_cvt_pk_bf16_f32 v51, v56, v57
	global_store_dwordx4 v[60:61], v[48:51], off offset:256
	s_nop 1
	v_add_u32_e32 v48, 0x90, v136
	v_ashrrev_i32_e32 v49, 31, v48
	v_lshl_add_u64 v[50:51], v[48:49], 2, s[30:31]
	s_nop 1
	s_waitcnt vmcnt(12)
	v_fmamk_f32 v49, v221, 0x3b800000, v147
	v_rsq_f32_e32 v50, v49
	s_nop 0
	v_pk_mul_f32 v[44:45], v[44:45], v[50:51] op_sel_hi:[1,0]
	v_pk_mul_f32 v[52:53], v[42:43], v[50:51] op_sel_hi:[1,0]
	v_pk_mul_f32 v[42:43], v[40:41], v[50:51] op_sel_hi:[1,0]
	v_cvt_pk_bf16_f32 v40, v44, v45
	v_mad_i64_i32 v[44:45], s[8:9], v48, s84, v[120:121]
	v_pk_mul_f32 v[46:47], v[46:47], v[50:51] op_sel_hi:[1,0]
	v_lshl_add_u64 v[44:45], v[44:45], 0, v[122:123]
	v_cvt_pk_bf16_f32 v41, v46, v47
	v_cvt_pk_bf16_f32 v42, v42, v43
	v_cvt_pk_bf16_f32 v43, v52, v53
	global_store_dwordx4 v[44:45], v[40:43], off
	v_pk_mul_f32 v[36:37], v[36:37], v[50:51] op_sel_hi:[1,0]
	v_pk_mul_f32 v[38:39], v[38:39], v[50:51] op_sel_hi:[1,0]
	v_pk_mul_f32 v[40:41], v[34:35], v[50:51] op_sel_hi:[1,0]
	v_pk_mul_f32 v[34:35], v[32:33], v[50:51] op_sel_hi:[1,0]
	v_cvt_pk_bf16_f32 v32, v36, v37
	v_cvt_pk_bf16_f32 v33, v38, v39
	s_nop 0
	v_cvt_pk_bf16_f32 v34, v34, v35
	v_cvt_pk_bf16_f32 v35, v40, v41
	global_store_dwordx4 v[44:45], v[32:35], off offset:256
	s_nop 1
	v_add_u32_e32 v32, 0xa0, v136
	v_ashrrev_i32_e32 v33, 31, v32
	v_lshl_add_u64 v[34:35], v[32:33], 2, s[30:31]
	s_nop 1
	s_waitcnt vmcnt(13)
	v_fmamk_f32 v33, v222, 0x3b800000, v147
	v_rsq_f32_e32 v34, v33
	s_nop 0
	v_pk_mul_f32 v[28:29], v[28:29], v[34:35] op_sel_hi:[1,0]
	v_pk_mul_f32 v[36:37], v[26:27], v[34:35] op_sel_hi:[1,0]
	v_pk_mul_f32 v[26:27], v[24:25], v[34:35] op_sel_hi:[1,0]
	v_cvt_pk_bf16_f32 v24, v28, v29
	v_mad_i64_i32 v[28:29], s[8:9], v32, s84, v[120:121]
	v_pk_mul_f32 v[30:31], v[30:31], v[34:35] op_sel_hi:[1,0]
	v_lshl_add_u64 v[28:29], v[28:29], 0, v[122:123]
	v_cvt_pk_bf16_f32 v25, v30, v31
	v_cvt_pk_bf16_f32 v26, v26, v27
	v_cvt_pk_bf16_f32 v27, v36, v37
	global_store_dwordx4 v[28:29], v[24:27], off
	v_pk_mul_f32 v[20:21], v[20:21], v[34:35] op_sel_hi:[1,0]
	v_pk_mul_f32 v[22:23], v[22:23], v[34:35] op_sel_hi:[1,0]
	v_pk_mul_f32 v[24:25], v[18:19], v[34:35] op_sel_hi:[1,0]
	v_pk_mul_f32 v[18:19], v[16:17], v[34:35] op_sel_hi:[1,0]
	v_cvt_pk_bf16_f32 v16, v20, v21
	v_cvt_pk_bf16_f32 v17, v22, v23
	s_nop 0
	v_cvt_pk_bf16_f32 v18, v18, v19
	v_cvt_pk_bf16_f32 v19, v24, v25
	global_store_dwordx4 v[28:29], v[16:19], off offset:256
	s_nop 1
	v_add_u32_e32 v16, 0xb0, v136
	v_ashrrev_i32_e32 v17, 31, v16
	v_lshl_add_u64 v[18:19], v[16:17], 2, s[30:31]
	s_nop 1
	s_waitcnt vmcnt(14)
	v_fmamk_f32 v17, v223, 0x3b800000, v147
	v_rsq_f32_e32 v18, v17
	s_nop 0
	v_pk_mul_f32 v[12:13], v[12:13], v[18:19] op_sel_hi:[1,0]
	v_pk_mul_f32 v[20:21], v[10:11], v[18:19] op_sel_hi:[1,0]
	v_pk_mul_f32 v[10:11], v[8:9], v[18:19] op_sel_hi:[1,0]
	v_cvt_pk_bf16_f32 v8, v12, v13
	v_mad_i64_i32 v[12:13], s[8:9], v16, s84, v[120:121]
	v_pk_mul_f32 v[14:15], v[14:15], v[18:19] op_sel_hi:[1,0]
	v_lshl_add_u64 v[12:13], v[12:13], 0, v[122:123]
	v_cvt_pk_bf16_f32 v9, v14, v15
	v_cvt_pk_bf16_f32 v10, v10, v11
	v_cvt_pk_bf16_f32 v11, v20, v21
	global_store_dwordx4 v[12:13], v[8:11], off
	v_pk_mul_f32 v[6:7], v[6:7], v[18:19] op_sel_hi:[1,0]
	v_pk_mul_f32 v[4:5], v[4:5], v[18:19] op_sel_hi:[1,0]
	v_pk_mul_f32 v[8:9], v[2:3], v[18:19] op_sel_hi:[1,0]
	v_pk_mul_f32 v[2:3], v[0:1], v[18:19] op_sel_hi:[1,0]
	v_cvt_pk_bf16_f32 v0, v4, v5
	v_cvt_pk_bf16_f32 v1, v6, v7
	s_mov_b64 s[8:9], -1
	v_cvt_pk_bf16_f32 v2, v2, v3
	v_cvt_pk_bf16_f32 v3, v8, v9
	global_store_dwordx4 v[12:13], v[0:3], off offset:256
	s_cbranch_vccnz .LBB0_350
	s_andn2_b64 vcc, exec, s[0:1]
	s_cbranch_vccnz .LBB0_349
	s_barrier
	s_branch .LBB0_349

; __device__ __forceinline__ u32x4 pack8(f32x4 v0, f32x4 v1) { u32x4 w; w.x = cvt_pk_bf16(v0[0], v0[1]); w.y = cvt_pk_bf16(v0[2], v0[3]); w.z = cvt_pk_bf16(v1[0], v1[1]); w.w = cvt_pk_bf16(v1[2], v1[3]); return w; }
;     __device__ __forceinline__ void operator()(EPI_ARGS) const {
; #pragma unroll
;         for (int ai = 0; ai < 2; ++ai)
; #pragma unroll
;             for (int m = 0; m < 4; ++m) { const int row = EPI_ROW(ai, m); const float rs = __builtin_amdgcn_rsqf(rsqs[row] * (1.f / 1024.f) + RMS_EPS);
; #pragma unroll
;                 for (int bj = 0; bj < 2; ++bj) *(u32x4*)(O + (size_t)row * 2048 + EPI_COL(bj)) = pack8(acc[ai][bj][m][0] * rs, acc[ai][bj][m][1] * rs);
;                 asm volatile("" ::: "memory"); }
;     }
.LBB0_774:
	v_ashrrev_i32_e32 v137, 31, v136
	v_lshl_add_u64 v[2:3], v[136:137], 2, s[64:65]
	global_load_dword v216, v[2:3], off
	global_load_dword v217, v[2:3], off offset:64
	global_load_dword v218, v[2:3], off offset:128
	global_load_dword v219, v[2:3], off offset:192
	global_load_dword v220, v[2:3], off offset:512
	global_load_dword v221, v[2:3], off offset:576
	global_load_dword v222, v[2:3], off offset:640
	global_load_dword v223, v[2:3], off offset:704
	v_lshl_or_b32 v2, s53, 8, v151
	v_lshlrev_b64 v[156:157], 12, v[136:137]
	v_ashrrev_i32_e32 v3, 31, v2
	v_lshl_add_u64 v[156:157], s[86:87], 0, v[156:157]
	v_lshlrev_b64 v[2:3], 1, v[2:3]
	v_or_b32_e32 v138, 16, v136
	v_lshl_add_u64 v[156:157], v[156:157], 0, v[2:3]
	v_ashrrev_i32_e32 v139, 31, v138
	v_lshl_add_u64 v[166:167], v[138:139], 2, s[64:65]
	s_andn2_b64 vcc, exec, s[0:1]
	s_mov_b64 s[0:1], -1
	s_waitcnt vmcnt(7)
	v_fmamk_f32 v1, v216, 0x3a800000, v152
	v_rsq_f32_e32 v158, v1
	s_nop 0
	v_pk_mul_f32 v[130:131], v[130:131], v[158:159] op_sel_hi:[1,0]
	v_pk_mul_f32 v[128:129], v[128:129], v[158:159] op_sel_hi:[1,0]
	v_pk_mul_f32 v[126:127], v[126:127], v[158:159] op_sel_hi:[1,0]
	v_pk_mul_f32 v[124:125], v[124:125], v[158:159] op_sel_hi:[1,0]
	v_pk_mul_f32 v[122:123], v[122:123], v[158:159] op_sel_hi:[1,0]
	v_pk_mul_f32 v[120:121], v[120:121], v[158:159] op_sel_hi:[1,0]
	v_pk_mul_f32 v[172:173], v[118:119], v[158:159] op_sel_hi:[1,0]
	v_pk_mul_f32 v[158:159], v[116:117], v[158:159] op_sel_hi:[1,0]
	v_cvt_pk_bf16_f32 v116, v128, v129
	v_cvt_pk_bf16_f32 v117, v130, v131
	v_cvt_pk_bf16_f32 v118, v124, v125
	v_cvt_pk_bf16_f32 v119, v126, v127
	global_store_dwordx4 v[156:157], v[116:119], off
	s_nop 1
	v_cvt_pk_bf16_f32 v116, v120, v121
	v_cvt_pk_bf16_f32 v117, v122, v123
	v_cvt_pk_bf16_f32 v118, v158, v159
	v_cvt_pk_bf16_f32 v119, v172, v173
	global_store_dwordx4 v[156:157], v[116:119], off offset:256
	s_nop 1
	s_waitcnt vmcnt(8)
	v_fmamk_f32 v1, v217, 0x3a800000, v152
	v_rsq_f32_e32 v120, v1
	v_lshlrev_b64 v[118:119], 12, v[138:139]
	v_lshl_add_u64 v[118:119], s[86:87], 0, v[118:119]
	v_or_b32_e32 v116, 32, v136
	v_lshl_add_u64 v[118:119], v[118:119], 0, v[2:3]
	v_pk_mul_f32 v[114:115], v[114:115], v[120:121] op_sel_hi:[1,0]
	v_pk_mul_f32 v[112:113], v[112:113], v[120:121] op_sel_hi:[1,0]
	v_pk_mul_f32 v[110:111], v[110:111], v[120:121] op_sel_hi:[1,0]
	v_pk_mul_f32 v[108:109], v[108:109], v[120:121] op_sel_hi:[1,0]
	v_pk_mul_f32 v[106:107], v[106:107], v[120:121] op_sel_hi:[1,0]
	v_pk_mul_f32 v[104:105], v[104:105], v[120:121] op_sel_hi:[1,0]
	v_pk_mul_f32 v[124:125], v[102:103], v[120:121] op_sel_hi:[1,0]
	v_pk_mul_f32 v[120:121], v[100:101], v[120:121] op_sel_hi:[1,0]
	v_cvt_pk_bf16_f32 v100, v112, v113
	v_cvt_pk_bf16_f32 v101, v114, v115
	v_cvt_pk_bf16_f32 v102, v108, v109
	v_cvt_pk_bf16_f32 v103, v110, v111
	v_ashrrev_i32_e32 v117, 31, v116
	global_store_dwordx4 v[118:119], v[100:103], off
	v_lshl_add_u64 v[122:123], v[116:117], 2, s[64:65]
	s_nop 0
	v_cvt_pk_bf16_f32 v100, v104, v105
	v_cvt_pk_bf16_f32 v101, v106, v107
	v_cvt_pk_bf16_f32 v102, v120, v121
	v_cvt_pk_bf16_f32 v103, v124, v125
	global_store_dwordx4 v[118:119], v[100:103], off offset:256
	s_nop 1
	s_waitcnt vmcnt(9)
	v_fmamk_f32 v1, v218, 0x3a800000, v152
	v_rsq_f32_e32 v104, v1
	v_lshlrev_b64 v[102:103], 12, v[116:117]
	v_lshl_add_u64 v[102:103], s[86:87], 0, v[102:103]
	v_or_b32_e32 v100, 48, v136
	v_lshl_add_u64 v[102:103], v[102:103], 0, v[2:3]
	v_pk_mul_f32 v[98:99], v[98:99], v[104:105] op_sel_hi:[1,0]
	v_pk_mul_f32 v[96:97], v[96:97], v[104:105] op_sel_hi:[1,0]
	v_pk_mul_f32 v[94:95], v[94:95], v[104:105] op_sel_hi:[1,0]
	v_pk_mul_f32 v[92:93], v[92:93], v[104:105] op_sel_hi:[1,0]
	v_pk_mul_f32 v[90:91], v[90:91], v[104:105] op_sel_hi:[1,0]
	v_pk_mul_f32 v[88:89], v[88:89], v[104:105] op_sel_hi:[1,0]
	v_pk_mul_f32 v[108:109], v[86:87], v[104:105] op_sel_hi:[1,0]
	v_pk_mul_f32 v[104:105], v[84:85], v[104:105] op_sel_hi:[1,0]
	v_cvt_pk_bf16_f32 v84, v96, v97
	v_cvt_pk_bf16_f32 v85, v98, v99
	v_cvt_pk_bf16_f32 v86, v92, v93
	v_cvt_pk_bf16_f32 v87, v94, v95
	v_ashrrev_i32_e32 v101, 31, v100
	global_store_dwordx4 v[102:103], v[84:87], off
	v_lshl_add_u64 v[106:107], v[100:101], 2, s[64:65]
	s_nop 0
	v_cvt_pk_bf16_f32 v84, v88, v89
	v_cvt_pk_bf16_f32 v85, v90, v91
	v_cvt_pk_bf16_f32 v86, v104, v105
	v_cvt_pk_bf16_f32 v87, v108, v109
	global_store_dwordx4 v[102:103], v[84:87], off offset:256
	s_nop 1
	s_waitcnt vmcnt(10)
	v_fmamk_f32 v1, v219, 0x3a800000, v152
	v_rsq_f32_e32 v88, v1
	v_lshlrev_b64 v[86:87], 12, v[100:101]
	v_lshl_add_u64 v[86:87], s[86:87], 0, v[86:87]
	v_add_u32_e32 v84, 0x80, v136
	v_lshl_add_u64 v[86:87], v[86:87], 0, v[2:3]
	v_pk_mul_f32 v[82:83], v[82:83], v[88:89] op_sel_hi:[1,0]
	v_pk_mul_f32 v[80:81], v[80:81], v[88:89] op_sel_hi:[1,0]
	v_pk_mul_f32 v[78:79], v[78:79], v[88:89] op_sel_hi:[1,0]
	v_pk_mul_f32 v[76:77], v[76:77], v[88:89] op_sel_hi:[1,0]
	v_pk_mul_f32 v[74:75], v[74:75], v[88:89] op_sel_hi:[1,0]
	v_pk_mul_f32 v[72:73], v[72:73], v[88:89] op_sel_hi:[1,0]
	v_pk_mul_f32 v[92:93], v[70:71], v[88:89] op_sel_hi:[1,0]
	v_pk_mul_f32 v[88:89], v[68:69], v[88:89] op_sel_hi:[1,0]
	v_cvt_pk_bf16_f32 v68, v80, v81
	v_cvt_pk_bf16_f32 v69, v82, v83
	v_cvt_pk_bf16_f32 v70, v76, v77
	v_cvt_pk_bf16_f32 v71, v78, v79
	v_ashrrev_i32_e32 v85, 31, v84
	global_store_dwordx4 v[86:87], v[68:71], off
	v_lshl_add_u64 v[90:91], v[84:85], 2, s[64:65]
	s_nop 0
	v_cvt_pk_bf16_f32 v68, v72, v73
	v_cvt_pk_bf16_f32 v69, v74, v75
	v_cvt_pk_bf16_f32 v70, v88, v89
	v_cvt_pk_bf16_f32 v71, v92, v93
	global_store_dwordx4 v[86:87], v[68:71], off offset:256
	s_nop 1
	s_waitcnt vmcnt(11)
; __device__ __forceinline__ u32x4 pack8(f32x4 v0, f32x4 v1) { u32x4 w; w.x = cvt_pk_bf16(v0[0], v0[1]); w.y = cvt_pk_bf16(v0[2], v0[3]); w.z = cvt_pk_bf16(v1[0], v1[1]); w.w = cvt_pk_bf16(v1[2], v1[3]); return w; }
;     __device__ __forceinline__ void operator()(EPI_ARGS) const {
; #pragma unroll
;         for (int ai = 0; ai < 2; ++ai)
; #pragma unroll
;             for (int m = 0; m < 4; ++m) { const int row = EPI_ROW(ai, m); const float rs = __builtin_amdgcn_rsqf(rsqs[row] * (1.f / 1024.f) + RMS_EPS);
; #pragma unroll
;                 for (int bj = 0; bj < 2; ++bj) *(u32x4*)(O + (size_t)row * 2048 + EPI_COL(bj)) = pack8(acc[ai][bj][m][0] * rs, acc[ai][bj][m][1] * rs);
;                 asm volatile("" ::: "memory"); }
;     }
	v_fmamk_f32 v1, v220, 0x3a800000, v152
	v_rsq_f32_e32 v72, v1
	v_lshlrev_b64 v[70:71], 12, v[84:85]
	v_lshl_add_u64 v[70:71], s[86:87], 0, v[70:71]
	v_add_u32_e32 v68, 0x90, v136
	v_lshl_add_u64 v[70:71], v[70:71], 0, v[2:3]
	v_pk_mul_f32 v[66:67], v[66:67], v[72:73] op_sel_hi:[1,0]
	v_pk_mul_f32 v[64:65], v[64:65], v[72:73] op_sel_hi:[1,0]
	v_pk_mul_f32 v[62:63], v[62:63], v[72:73] op_sel_hi:[1,0]
	v_pk_mul_f32 v[60:61], v[60:61], v[72:73] op_sel_hi:[1,0]
	v_pk_mul_f32 v[58:59], v[58:59], v[72:73] op_sel_hi:[1,0]
	v_pk_mul_f32 v[56:57], v[56:57], v[72:73] op_sel_hi:[1,0]
	v_pk_mul_f32 v[76:77], v[54:55], v[72:73] op_sel_hi:[1,0]
	v_pk_mul_f32 v[72:73], v[52:53], v[72:73] op_sel_hi:[1,0]
	v_cvt_pk_bf16_f32 v52, v64, v65
	v_cvt_pk_bf16_f32 v53, v66, v67
	v_cvt_pk_bf16_f32 v54, v60, v61
	v_cvt_pk_bf16_f32 v55, v62, v63
	v_ashrrev_i32_e32 v69, 31, v68
	global_store_dwordx4 v[70:71], v[52:55], off
	v_lshl_add_u64 v[74:75], v[68:69], 2, s[64:65]
	s_nop 0
	v_cvt_pk_bf16_f32 v52, v56, v57
	v_cvt_pk_bf16_f32 v53, v58, v59
	v_cvt_pk_bf16_f32 v54, v72, v73
	v_cvt_pk_bf16_f32 v55, v76, v77
	global_store_dwordx4 v[70:71], v[52:55], off offset:256
	s_nop 1
	s_waitcnt vmcnt(12)
	v_fmamk_f32 v1, v221, 0x3a800000, v152
	v_rsq_f32_e32 v56, v1
	v_lshlrev_b64 v[54:55], 12, v[68:69]
	v_lshl_add_u64 v[54:55], s[86:87], 0, v[54:55]
	v_add_u32_e32 v52, 0xa0, v136
	v_lshl_add_u64 v[54:55], v[54:55], 0, v[2:3]
	v_pk_mul_f32 v[50:51], v[50:51], v[56:57] op_sel_hi:[1,0]
	v_pk_mul_f32 v[48:49], v[48:49], v[56:57] op_sel_hi:[1,0]
	v_pk_mul_f32 v[46:47], v[46:47], v[56:57] op_sel_hi:[1,0]
	v_pk_mul_f32 v[44:45], v[44:45], v[56:57] op_sel_hi:[1,0]
	v_pk_mul_f32 v[42:43], v[42:43], v[56:57] op_sel_hi:[1,0]
	v_pk_mul_f32 v[40:41], v[40:41], v[56:57] op_sel_hi:[1,0]
	v_pk_mul_f32 v[60:61], v[38:39], v[56:57] op_sel_hi:[1,0]
	v_pk_mul_f32 v[56:57], v[36:37], v[56:57] op_sel_hi:[1,0]
	v_cvt_pk_bf16_f32 v36, v48, v49
	v_cvt_pk_bf16_f32 v37, v50, v51
	v_cvt_pk_bf16_f32 v38, v44, v45
	v_cvt_pk_bf16_f32 v39, v46, v47
	v_ashrrev_i32_e32 v53, 31, v52
	global_store_dwordx4 v[54:55], v[36:39], off
	v_lshl_add_u64 v[58:59], v[52:53], 2, s[64:65]
	s_nop 0
	v_cvt_pk_bf16_f32 v36, v40, v41
	v_cvt_pk_bf16_f32 v37, v42, v43
	v_cvt_pk_bf16_f32 v38, v56, v57
	v_cvt_pk_bf16_f32 v39, v60, v61
	global_store_dwordx4 v[54:55], v[36:39], off offset:256
	s_nop 1
	s_waitcnt vmcnt(13)
	v_fmamk_f32 v1, v222, 0x3a800000, v152
	v_rsq_f32_e32 v40, v1
	v_lshlrev_b64 v[38:39], 12, v[52:53]
	v_lshl_add_u64 v[38:39], s[86:87], 0, v[38:39]
	v_add_u32_e32 v36, 0xb0, v136
	v_lshl_add_u64 v[38:39], v[38:39], 0, v[2:3]
	v_pk_mul_f32 v[34:35], v[34:35], v[40:41] op_sel_hi:[1,0]
	v_pk_mul_f32 v[32:33], v[32:33], v[40:41] op_sel_hi:[1,0]
	v_pk_mul_f32 v[30:31], v[30:31], v[40:41] op_sel_hi:[1,0]
	v_pk_mul_f32 v[28:29], v[28:29], v[40:41] op_sel_hi:[1,0]
	v_pk_mul_f32 v[26:27], v[26:27], v[40:41] op_sel_hi:[1,0]
	v_pk_mul_f32 v[24:25], v[24:25], v[40:41] op_sel_hi:[1,0]
	v_pk_mul_f32 v[44:45], v[22:23], v[40:41] op_sel_hi:[1,0]
	v_pk_mul_f32 v[40:41], v[20:21], v[40:41] op_sel_hi:[1,0]
	v_cvt_pk_bf16_f32 v20, v32, v33
	v_cvt_pk_bf16_f32 v21, v34, v35
	v_cvt_pk_bf16_f32 v22, v28, v29
	v_cvt_pk_bf16_f32 v23, v30, v31
	v_ashrrev_i32_e32 v37, 31, v36
	global_store_dwordx4 v[38:39], v[20:23], off
	v_lshl_add_u64 v[42:43], v[36:37], 2, s[64:65]
	s_nop 0
	v_cvt_pk_bf16_f32 v20, v24, v25
	v_cvt_pk_bf16_f32 v21, v26, v27
	v_cvt_pk_bf16_f32 v22, v40, v41
	v_cvt_pk_bf16_f32 v23, v44, v45
	global_store_dwordx4 v[38:39], v[20:23], off offset:256
	s_nop 1
	s_waitcnt vmcnt(14)
	v_fmamk_f32 v1, v223, 0x3a800000, v152
	v_rsq_f32_e32 v20, v1
	v_lshlrev_b64 v[22:23], 12, v[36:37]
	v_lshl_add_u64 v[22:23], s[86:87], 0, v[22:23]
	v_lshl_add_u64 v[22:23], v[22:23], 0, v[2:3]
	v_pk_mul_f32 v[2:3], v[16:17], v[20:21] op_sel_hi:[1,0]
	v_pk_mul_f32 v[18:19], v[18:19], v[20:21] op_sel_hi:[1,0]
	v_pk_mul_f32 v[14:15], v[14:15], v[20:21] op_sel_hi:[1,0]
	v_pk_mul_f32 v[12:13], v[12:13], v[20:21] op_sel_hi:[1,0]
	v_pk_mul_f32 v[16:17], v[4:5], v[20:21] op_sel_hi:[1,0]
	v_cvt_pk_bf16_f32 v2, v2, v3
	v_cvt_pk_bf16_f32 v3, v18, v19
	v_cvt_pk_bf16_f32 v4, v12, v13
	v_cvt_pk_bf16_f32 v5, v14, v15
	v_pk_mul_f32 v[10:11], v[10:11], v[20:21] op_sel_hi:[1,0]
	v_pk_mul_f32 v[8:9], v[8:9], v[20:21] op_sel_hi:[1,0]
	v_pk_mul_f32 v[6:7], v[6:7], v[20:21] op_sel_hi:[1,0]
	global_store_dwordx4 v[22:23], v[2:5], off
	s_nop 1
	v_cvt_pk_bf16_f32 v2, v8, v9
	v_cvt_pk_bf16_f32 v3, v10, v11
	v_cvt_pk_bf16_f32 v4, v16, v17
	v_cvt_pk_bf16_f32 v5, v6, v7
	global_store_dwordx4 v[22:23], v[2:5], off offset:256
	s_cbranch_vccnz .LBB0_765
	s_andn2_b64 vcc, exec, s[8:9]
	s_cbranch_vccnz .LBB0_764
	s_barrier
	s_branch .LBB0_764
